# v26 + recurrence operand prefetch distance 2 (three rotating operand sets, counted lgkmcnt waits)
# baseline (speedup 1.0000x reference)
.LBB0_1238:
	s_or_b64 exec, exec, s[18:19]
	s_waitcnt lgkmcnt(0)
	s_barrier
	s_cmp_lg_u32 s100, 0
	s_cselect_b32 s97, 0x800, 0
	v_add_u32_e32 v167, s97, v114
	ds_read_b128 v[72:75], v114 offset:41216
	ds_read_b128 v[68:71], v114 offset:45312
	ds_read_b128 v[64:67], v114 offset:49408
	ds_read_b128 v[56:59], v114 offset:53504
	ds_read_b128 v[60:63], v167 offset:28928
	ds_read2st64_b32 v[214:215], v115 offset0:0 offset1:1
	ds_read_b128 v[134:137], v114 offset:41344
	ds_read_b128 v[138:141], v114 offset:45440
	ds_read_b128 v[142:145], v114 offset:49536
	ds_read_b128 v[146:149], v114 offset:53632
	ds_read_b128 v[130:133], v167 offset:29056
	s_waitcnt lgkmcnt(5)
	v_dot2_f32_f16 v151, v127, v72, 0
	v_dot2_f32_f16 v151, v126, v73, v151
	v_dot2_f32_f16 v151, v125, v74, v151
	v_dot2_f32_f16 v151, v124, v75, v151
	ds_read2st64_b32 v[216:217], v115 offset0:2 offset1:3
	ds_read_b128 v[224:227], v114 offset:41472
	ds_read_b128 v[228:231], v114 offset:45568
	v_add_f32_dpp v151, v151, v151 quad_perm:[1,0,3,2] row_mask:0xf bank_mask:0xf bound_ctrl:1
	ds_read_b128 v[232:235], v114 offset:49664
	ds_read_b128 v[220:223], v167 offset:29184
	v_add_f32_dpp v151, v151, v151 quad_perm:[2,3,0,1] row_mask:0xf bank_mask:0xf bound_ctrl:1
	ds_read_b128 v[236:239], v114 offset:53760
	s_nop 0
	v_add_f32_dpp v151, v151, v151 row_half_mirror row_mask:0xf bank_mask:0xf bound_ctrl:1
	v_cvt_pkrtz_f16_f32 v152, -v151, -v151
	v_pk_mul_f16 v153, v152, v68
	v_pk_mul_f16 v154, v152, v69
	v_pk_mul_f16 v155, v152, v70
	v_pk_mul_f16 v156, v152, v71
	v_pk_fma_f16 v153, v214, v64, v153
	v_pk_fma_f16 v154, v214, v65, v154
	v_pk_fma_f16 v155, v214, v66, v155
	v_pk_fma_f16 v156, v214, v67, v156
	v_pk_fma_f16 v127, v127, v60, v153
	v_pk_fma_f16 v126, v126, v61, v154
	v_pk_fma_f16 v125, v125, v62, v155
	v_pk_fma_f16 v124, v124, v63, v156
	s_waitcnt lgkmcnt(6)
	v_dot2_f32_f16 v151, v127, v134, 0
	v_dot2_f32_f16 v151, v126, v135, v151
	v_dot2_f32_f16 v151, v125, v136, v151
	v_dot2_f32_f16 v151, v124, v137, v151
	v_dot2_f32_f16 v157, v127, v56, 0
	v_dot2_f32_f16 v157, v126, v57, v157
	v_dot2_f32_f16 v157, v125, v58, v157
	v_dot2_f32_f16 v157, v124, v59, v157
	v_add_f32_dpp v151, v151, v151 quad_perm:[1,0,3,2] row_mask:0xf bank_mask:0xf bound_ctrl:1
	ds_read_b128 v[72:75], v114 offset:41600
	ds_read_b128 v[68:71], v114 offset:45696
	v_add_f32_dpp v151, v151, v151 quad_perm:[2,3,0,1] row_mask:0xf bank_mask:0xf bound_ctrl:1
	ds_read_b128 v[64:67], v114 offset:49792
	ds_read_b128 v[60:63], v167 offset:29312
	ds_read_b128 v[56:59], v114 offset:53888
	v_add_f32_dpp v151, v151, v151 row_half_mirror row_mask:0xf bank_mask:0xf bound_ctrl:1
	v_cvt_pkrtz_f16_f32 v152, -v151, -v151
	v_pk_mul_f16 v153, v152, v138
	v_pk_mul_f16 v154, v152, v139
	v_pk_mul_f16 v155, v152, v140
	v_pk_mul_f16 v156, v152, v141
	v_pk_fma_f16 v153, v215, v142, v153
	v_pk_fma_f16 v154, v215, v143, v154
	v_pk_fma_f16 v155, v215, v144, v155
	v_pk_fma_f16 v156, v215, v145, v156
	v_pk_fma_f16 v127, v127, v130, v153
	v_pk_fma_f16 v126, v126, v131, v154
	v_pk_fma_f16 v125, v125, v132, v155
	v_pk_fma_f16 v124, v124, v133, v156
	s_waitcnt lgkmcnt(5)
	v_dot2_f32_f16 v151, v127, v224, 0
	v_dot2_f32_f16 v151, v126, v225, v151
	v_dot2_f32_f16 v151, v125, v226, v151
	v_dot2_f32_f16 v151, v124, v227, v151
	v_dot2_f32_f16 v158, v127, v146, 0
	v_dot2_f32_f16 v158, v126, v147, v158
	v_dot2_f32_f16 v158, v125, v148, v158
	v_dot2_f32_f16 v158, v124, v149, v158
	v_add_f32_dpp v151, v151, v151 quad_perm:[1,0,3,2] row_mask:0xf bank_mask:0xf bound_ctrl:1
	ds_read2st64_b32 v[214:215], v115 offset0:4 offset1:5
	ds_read_b128 v[134:137], v114 offset:41728
	ds_read_b128 v[138:141], v114 offset:45824
	v_add_f32_dpp v151, v151, v151 quad_perm:[2,3,0,1] row_mask:0xf bank_mask:0xf bound_ctrl:1
	ds_read_b128 v[142:145], v114 offset:49920
	ds_read_b128 v[130:133], v167 offset:29440
	ds_read_b128 v[146:149], v114 offset:54016
	ds_write2st64_b32 v116, v157, v158 offset0:0 offset1:8
	v_add_f32_dpp v151, v151, v151 row_half_mirror row_mask:0xf bank_mask:0xf bound_ctrl:1
	v_cvt_pkrtz_f16_f32 v152, -v151, -v151
	v_pk_mul_f16 v153, v152, v228
	v_pk_mul_f16 v154, v152, v229
	v_pk_mul_f16 v155, v152, v230
	v_pk_mul_f16 v156, v152, v231
	v_pk_fma_f16 v153, v216, v232, v153
	v_pk_fma_f16 v154, v216, v233, v154
	v_pk_fma_f16 v155, v216, v234, v155
	v_pk_fma_f16 v156, v216, v235, v156
	v_pk_fma_f16 v127, v127, v220, v153
	v_pk_fma_f16 v126, v126, v221, v154
	v_pk_fma_f16 v125, v125, v222, v155
	v_pk_fma_f16 v124, v124, v223, v156
	s_waitcnt lgkmcnt(7)
	v_dot2_f32_f16 v151, v127, v72, 0
	v_dot2_f32_f16 v151, v126, v73, v151
	v_dot2_f32_f16 v151, v125, v74, v151
	v_dot2_f32_f16 v151, v124, v75, v151
	v_dot2_f32_f16 v157, v127, v236, 0
	v_dot2_f32_f16 v157, v126, v237, v157
	v_dot2_f32_f16 v157, v125, v238, v157
	v_dot2_f32_f16 v157, v124, v239, v157
	v_add_f32_dpp v151, v151, v151 quad_perm:[1,0,3,2] row_mask:0xf bank_mask:0xf bound_ctrl:1
	ds_read_b128 v[224:227], v114 offset:41856
	ds_read_b128 v[228:231], v114 offset:45952
	v_add_f32_dpp v151, v151, v151 quad_perm:[2,3,0,1] row_mask:0xf bank_mask:0xf bound_ctrl:1
	ds_read_b128 v[232:235], v114 offset:50048
	ds_read_b128 v[220:223], v167 offset:29568
	ds_read_b128 v[236:239], v114 offset:54144
	v_add_f32_dpp v151, v151, v151 row_half_mirror row_mask:0xf bank_mask:0xf bound_ctrl:1
	v_cvt_pkrtz_f16_f32 v152, -v151, -v151
	v_pk_mul_f16 v153, v152, v68
	v_pk_mul_f16 v154, v152, v69
	v_pk_mul_f16 v155, v152, v70
	v_pk_mul_f16 v156, v152, v71
	v_pk_fma_f16 v153, v217, v64, v153
	v_pk_fma_f16 v154, v217, v65, v154
	v_pk_fma_f16 v155, v217, v66, v155
	v_pk_fma_f16 v156, v217, v67, v156
	v_pk_fma_f16 v127, v127, v60, v153
	v_pk_fma_f16 v126, v126, v61, v154
	v_pk_fma_f16 v125, v125, v62, v155
	v_pk_fma_f16 v124, v124, v63, v156
	s_waitcnt lgkmcnt(6)
	v_dot2_f32_f16 v151, v127, v134, 0
	v_dot2_f32_f16 v151, v126, v135, v151
	v_dot2_f32_f16 v151, v125, v136, v151
	v_dot2_f32_f16 v151, v124, v137, v151
	v_dot2_f32_f16 v158, v127, v56, 0
	v_dot2_f32_f16 v158, v126, v57, v158
	v_dot2_f32_f16 v158, v125, v58, v158
	v_dot2_f32_f16 v158, v124, v59, v158
	v_add_f32_dpp v151, v151, v151 quad_perm:[1,0,3,2] row_mask:0xf bank_mask:0xf bound_ctrl:1
	ds_read2st64_b32 v[216:217], v115 offset0:6 offset1:7
	ds_read_b128 v[72:75], v114 offset:41984
	ds_read_b128 v[68:71], v114 offset:46080
	v_add_f32_dpp v151, v151, v151 quad_perm:[2,3,0,1] row_mask:0xf bank_mask:0xf bound_ctrl:1
	ds_read_b128 v[64:67], v114 offset:50176
	ds_read_b128 v[60:63], v167 offset:29696
	ds_read_b128 v[56:59], v114 offset:54272
	ds_write2st64_b32 v116, v157, v158 offset0:16 offset1:24
	v_add_f32_dpp v151, v151, v151 row_half_mirror row_mask:0xf bank_mask:0xf bound_ctrl:1
	v_cvt_pkrtz_f16_f32 v152, -v151, -v151
	v_pk_mul_f16 v153, v152, v138
	v_pk_mul_f16 v154, v152, v139
	v_pk_mul_f16 v155, v152, v140
	v_pk_mul_f16 v156, v152, v141
	v_pk_fma_f16 v153, v214, v142, v153
	v_pk_fma_f16 v154, v214, v143, v154
	v_pk_fma_f16 v155, v214, v144, v155
	v_pk_fma_f16 v156, v214, v145, v156
	v_pk_fma_f16 v127, v127, v130, v153
	v_pk_fma_f16 v126, v126, v131, v154
	v_pk_fma_f16 v125, v125, v132, v155
	v_pk_fma_f16 v124, v124, v133, v156
	s_waitcnt lgkmcnt(7)
	v_dot2_f32_f16 v151, v127, v224, 0
	v_dot2_f32_f16 v151, v126, v225, v151
	v_dot2_f32_f16 v151, v125, v226, v151
	v_dot2_f32_f16 v151, v124, v227, v151
	v_dot2_f32_f16 v157, v127, v146, 0
	v_dot2_f32_f16 v157, v126, v147, v157
	v_dot2_f32_f16 v157, v125, v148, v157
	v_dot2_f32_f16 v157, v124, v149, v157
	v_add_f32_dpp v151, v151, v151 quad_perm:[1,0,3,2] row_mask:0xf bank_mask:0xf bound_ctrl:1
	ds_read_b128 v[134:137], v114 offset:42112
	ds_read_b128 v[138:141], v114 offset:46208
	v_add_f32_dpp v151, v151, v151 quad_perm:[2,3,0,1] row_mask:0xf bank_mask:0xf bound_ctrl:1
	ds_read_b128 v[142:145], v114 offset:50304
	ds_read_b128 v[130:133], v167 offset:29824
	ds_read_b128 v[146:149], v114 offset:54400
	v_add_f32_dpp v151, v151, v151 row_half_mirror row_mask:0xf bank_mask:0xf bound_ctrl:1
	v_cvt_pkrtz_f16_f32 v152, -v151, -v151
	v_pk_mul_f16 v153, v152, v228
	v_pk_mul_f16 v154, v152, v229
	v_pk_mul_f16 v155, v152, v230
	v_pk_mul_f16 v156, v152, v231
	v_pk_fma_f16 v153, v215, v232, v153
	v_pk_fma_f16 v154, v215, v233, v154
	v_pk_fma_f16 v155, v215, v234, v155
	v_pk_fma_f16 v156, v215, v235, v156
	v_pk_fma_f16 v127, v127, v220, v153
	v_pk_fma_f16 v126, v126, v221, v154
	v_pk_fma_f16 v125, v125, v222, v155
	v_pk_fma_f16 v124, v124, v223, v156
	s_waitcnt lgkmcnt(6)
	v_dot2_f32_f16 v151, v127, v72, 0
	v_dot2_f32_f16 v151, v126, v73, v151
	v_dot2_f32_f16 v151, v125, v74, v151
	v_dot2_f32_f16 v151, v124, v75, v151
	v_dot2_f32_f16 v158, v127, v236, 0
	v_dot2_f32_f16 v158, v126, v237, v158
	v_dot2_f32_f16 v158, v125, v238, v158
	v_dot2_f32_f16 v158, v124, v239, v158
	v_add_f32_dpp v151, v151, v151 quad_perm:[1,0,3,2] row_mask:0xf bank_mask:0xf bound_ctrl:1
	ds_read2st64_b32 v[214:215], v115 offset0:8 offset1:9
	ds_read_b128 v[224:227], v114 offset:42240
	ds_read_b128 v[228:231], v114 offset:46336
	v_add_f32_dpp v151, v151, v151 quad_perm:[2,3,0,1] row_mask:0xf bank_mask:0xf bound_ctrl:1
	ds_read_b128 v[232:235], v114 offset:50432
	ds_read_b128 v[220:223], v167 offset:29952
	ds_read_b128 v[236:239], v114 offset:54528
	ds_write2st64_b32 v116, v157, v158 offset0:32 offset1:40
	v_add_f32_dpp v151, v151, v151 row_half_mirror row_mask:0xf bank_mask:0xf bound_ctrl:1
	v_cvt_pkrtz_f16_f32 v152, -v151, -v151
	v_pk_mul_f16 v153, v152, v68
	v_pk_mul_f16 v154, v152, v69
	v_pk_mul_f16 v155, v152, v70
	v_pk_mul_f16 v156, v152, v71
	v_pk_fma_f16 v153, v216, v64, v153
	v_pk_fma_f16 v154, v216, v65, v154
	v_pk_fma_f16 v155, v216, v66, v155
	v_pk_fma_f16 v156, v216, v67, v156
	v_pk_fma_f16 v127, v127, v60, v153
	v_pk_fma_f16 v126, v126, v61, v154
	v_pk_fma_f16 v125, v125, v62, v155
	v_pk_fma_f16 v124, v124, v63, v156
	s_waitcnt lgkmcnt(7)
	v_dot2_f32_f16 v151, v127, v134, 0
	v_dot2_f32_f16 v151, v126, v135, v151
	v_dot2_f32_f16 v151, v125, v136, v151
	v_dot2_f32_f16 v151, v124, v137, v151
	v_dot2_f32_f16 v157, v127, v56, 0
	v_dot2_f32_f16 v157, v126, v57, v157
	v_dot2_f32_f16 v157, v125, v58, v157
	v_dot2_f32_f16 v157, v124, v59, v157
	v_add_f32_dpp v151, v151, v151 quad_perm:[1,0,3,2] row_mask:0xf bank_mask:0xf bound_ctrl:1
	ds_read_b128 v[72:75], v114 offset:42368
	ds_read_b128 v[68:71], v114 offset:46464
	v_add_f32_dpp v151, v151, v151 quad_perm:[2,3,0,1] row_mask:0xf bank_mask:0xf bound_ctrl:1
	ds_read_b128 v[64:67], v114 offset:50560
	ds_read_b128 v[60:63], v167 offset:30080
	ds_read_b128 v[56:59], v114 offset:54656
	v_add_f32_dpp v151, v151, v151 row_half_mirror row_mask:0xf bank_mask:0xf bound_ctrl:1
	v_cvt_pkrtz_f16_f32 v152, -v151, -v151
	v_pk_mul_f16 v153, v152, v138
	v_pk_mul_f16 v154, v152, v139
	v_pk_mul_f16 v155, v152, v140
	v_pk_mul_f16 v156, v152, v141
	v_pk_fma_f16 v153, v217, v142, v153
	v_pk_fma_f16 v154, v217, v143, v154
	v_pk_fma_f16 v155, v217, v144, v155
	v_pk_fma_f16 v156, v217, v145, v156
	v_pk_fma_f16 v127, v127, v130, v153
	v_pk_fma_f16 v126, v126, v131, v154
	v_pk_fma_f16 v125, v125, v132, v155
	v_pk_fma_f16 v124, v124, v133, v156
	s_waitcnt lgkmcnt(6)
	v_dot2_f32_f16 v151, v127, v224, 0
	v_dot2_f32_f16 v151, v126, v225, v151
	v_dot2_f32_f16 v151, v125, v226, v151
	v_dot2_f32_f16 v151, v124, v227, v151
	v_dot2_f32_f16 v158, v127, v146, 0
	v_dot2_f32_f16 v158, v126, v147, v158
	v_dot2_f32_f16 v158, v125, v148, v158
	v_dot2_f32_f16 v158, v124, v149, v158
	v_add_f32_dpp v151, v151, v151 quad_perm:[1,0,3,2] row_mask:0xf bank_mask:0xf bound_ctrl:1
	ds_read2st64_b32 v[216:217], v115 offset0:10 offset1:11
	ds_read_b128 v[134:137], v114 offset:42496
	ds_read_b128 v[138:141], v114 offset:46592
	v_add_f32_dpp v151, v151, v151 quad_perm:[2,3,0,1] row_mask:0xf bank_mask:0xf bound_ctrl:1
	ds_read_b128 v[142:145], v114 offset:50688
	ds_read_b128 v[130:133], v167 offset:30208
	ds_read_b128 v[146:149], v114 offset:54784
	ds_write2st64_b32 v116, v157, v158 offset0:48 offset1:56
	v_add_f32_dpp v151, v151, v151 row_half_mirror row_mask:0xf bank_mask:0xf bound_ctrl:1
	v_cvt_pkrtz_f16_f32 v152, -v151, -v151
	v_pk_mul_f16 v153, v152, v228
	v_pk_mul_f16 v154, v152, v229
	v_pk_mul_f16 v155, v152, v230
	v_pk_mul_f16 v156, v152, v231
	v_pk_fma_f16 v153, v214, v232, v153
	v_pk_fma_f16 v154, v214, v233, v154
	v_pk_fma_f16 v155, v214, v234, v155
	v_pk_fma_f16 v156, v214, v235, v156
	v_pk_fma_f16 v127, v127, v220, v153
	v_pk_fma_f16 v126, v126, v221, v154
	v_pk_fma_f16 v125, v125, v222, v155
	v_pk_fma_f16 v124, v124, v223, v156
	s_waitcnt lgkmcnt(7)
	v_dot2_f32_f16 v151, v127, v72, 0
	v_dot2_f32_f16 v151, v126, v73, v151
	v_dot2_f32_f16 v151, v125, v74, v151
	v_dot2_f32_f16 v151, v124, v75, v151
	v_dot2_f32_f16 v157, v127, v236, 0
	v_dot2_f32_f16 v157, v126, v237, v157
	v_dot2_f32_f16 v157, v125, v238, v157
	v_dot2_f32_f16 v157, v124, v239, v157
	v_add_f32_dpp v151, v151, v151 quad_perm:[1,0,3,2] row_mask:0xf bank_mask:0xf bound_ctrl:1
	ds_read_b128 v[224:227], v114 offset:42624
	ds_read_b128 v[228:231], v114 offset:46720
	v_add_f32_dpp v151, v151, v151 quad_perm:[2,3,0,1] row_mask:0xf bank_mask:0xf bound_ctrl:1
	ds_read_b128 v[232:235], v114 offset:50816
	ds_read_b128 v[220:223], v167 offset:30336
	ds_read_b128 v[236:239], v114 offset:54912
	v_add_f32_dpp v151, v151, v151 row_half_mirror row_mask:0xf bank_mask:0xf bound_ctrl:1
	v_cvt_pkrtz_f16_f32 v152, -v151, -v151
	v_pk_mul_f16 v153, v152, v68
	v_pk_mul_f16 v154, v152, v69
	v_pk_mul_f16 v155, v152, v70
	v_pk_mul_f16 v156, v152, v71
	v_pk_fma_f16 v153, v215, v64, v153
	v_pk_fma_f16 v154, v215, v65, v154
	v_pk_fma_f16 v155, v215, v66, v155
	v_pk_fma_f16 v156, v215, v67, v156
	v_pk_fma_f16 v127, v127, v60, v153
	v_pk_fma_f16 v126, v126, v61, v154
	v_pk_fma_f16 v125, v125, v62, v155
	v_pk_fma_f16 v124, v124, v63, v156
	s_waitcnt lgkmcnt(6)
	v_dot2_f32_f16 v151, v127, v134, 0
	v_dot2_f32_f16 v151, v126, v135, v151
	v_dot2_f32_f16 v151, v125, v136, v151
	v_dot2_f32_f16 v151, v124, v137, v151
	v_dot2_f32_f16 v158, v127, v56, 0
	v_dot2_f32_f16 v158, v126, v57, v158
	v_dot2_f32_f16 v158, v125, v58, v158
	v_dot2_f32_f16 v158, v124, v59, v158
	v_add_f32_dpp v151, v151, v151 quad_perm:[1,0,3,2] row_mask:0xf bank_mask:0xf bound_ctrl:1
	ds_read2st64_b32 v[214:215], v115 offset0:12 offset1:13
	ds_read_b128 v[72:75], v114 offset:42752
	ds_read_b128 v[68:71], v114 offset:46848
	v_add_f32_dpp v151, v151, v151 quad_perm:[2,3,0,1] row_mask:0xf bank_mask:0xf bound_ctrl:1
	ds_read_b128 v[64:67], v114 offset:50944
	ds_read_b128 v[60:63], v167 offset:30464
	ds_read_b128 v[56:59], v114 offset:55040
	ds_write2st64_b32 v116, v157, v158 offset0:64 offset1:72
	v_add_f32_dpp v151, v151, v151 row_half_mirror row_mask:0xf bank_mask:0xf bound_ctrl:1
	v_cvt_pkrtz_f16_f32 v152, -v151, -v151
	v_pk_mul_f16 v153, v152, v138
	v_pk_mul_f16 v154, v152, v139
	v_pk_mul_f16 v155, v152, v140
	v_pk_mul_f16 v156, v152, v141
	v_pk_fma_f16 v153, v216, v142, v153
	v_pk_fma_f16 v154, v216, v143, v154
	v_pk_fma_f16 v155, v216, v144, v155
	v_pk_fma_f16 v156, v216, v145, v156
	v_pk_fma_f16 v127, v127, v130, v153
	v_pk_fma_f16 v126, v126, v131, v154
	v_pk_fma_f16 v125, v125, v132, v155
	v_pk_fma_f16 v124, v124, v133, v156
	s_waitcnt lgkmcnt(7)
	v_dot2_f32_f16 v151, v127, v224, 0
	v_dot2_f32_f16 v151, v126, v225, v151
	v_dot2_f32_f16 v151, v125, v226, v151
	v_dot2_f32_f16 v151, v124, v227, v151
	v_dot2_f32_f16 v157, v127, v146, 0
	v_dot2_f32_f16 v157, v126, v147, v157
	v_dot2_f32_f16 v157, v125, v148, v157
	v_dot2_f32_f16 v157, v124, v149, v157
	v_add_f32_dpp v151, v151, v151 quad_perm:[1,0,3,2] row_mask:0xf bank_mask:0xf bound_ctrl:1
	ds_read_b128 v[134:137], v114 offset:42880
	ds_read_b128 v[138:141], v114 offset:46976
	v_add_f32_dpp v151, v151, v151 quad_perm:[2,3,0,1] row_mask:0xf bank_mask:0xf bound_ctrl:1
	ds_read_b128 v[142:145], v114 offset:51072
	ds_read_b128 v[130:133], v167 offset:30592
	ds_read_b128 v[146:149], v114 offset:55168
	v_add_f32_dpp v151, v151, v151 row_half_mirror row_mask:0xf bank_mask:0xf bound_ctrl:1
	v_cvt_pkrtz_f16_f32 v152, -v151, -v151
	v_pk_mul_f16 v153, v152, v228
	v_pk_mul_f16 v154, v152, v229
	v_pk_mul_f16 v155, v152, v230
	v_pk_mul_f16 v156, v152, v231
	v_pk_fma_f16 v153, v217, v232, v153
	v_pk_fma_f16 v154, v217, v233, v154
	v_pk_fma_f16 v155, v217, v234, v155
	v_pk_fma_f16 v156, v217, v235, v156
	v_pk_fma_f16 v127, v127, v220, v153
	v_pk_fma_f16 v126, v126, v221, v154
	v_pk_fma_f16 v125, v125, v222, v155
	v_pk_fma_f16 v124, v124, v223, v156
	s_waitcnt lgkmcnt(6)
	v_dot2_f32_f16 v151, v127, v72, 0
	v_dot2_f32_f16 v151, v126, v73, v151
	v_dot2_f32_f16 v151, v125, v74, v151
	v_dot2_f32_f16 v151, v124, v75, v151
	v_dot2_f32_f16 v158, v127, v236, 0
	v_dot2_f32_f16 v158, v126, v237, v158
	v_dot2_f32_f16 v158, v125, v238, v158
	v_dot2_f32_f16 v158, v124, v239, v158
	v_add_f32_dpp v151, v151, v151 quad_perm:[1,0,3,2] row_mask:0xf bank_mask:0xf bound_ctrl:1
	ds_read2st64_b32 v[216:217], v115 offset0:14 offset1:15
	ds_read_b128 v[224:227], v114 offset:43008
	ds_read_b128 v[228:231], v114 offset:47104
	v_add_f32_dpp v151, v151, v151 quad_perm:[2,3,0,1] row_mask:0xf bank_mask:0xf bound_ctrl:1
	ds_read_b128 v[232:235], v114 offset:51200
	ds_read_b128 v[220:223], v167 offset:30720
	ds_read_b128 v[236:239], v114 offset:55296
	ds_write2st64_b32 v116, v157, v158 offset0:80 offset1:88
	v_add_f32_dpp v151, v151, v151 row_half_mirror row_mask:0xf bank_mask:0xf bound_ctrl:1
	v_cvt_pkrtz_f16_f32 v152, -v151, -v151
	v_pk_mul_f16 v153, v152, v68
	v_pk_mul_f16 v154, v152, v69
	v_pk_mul_f16 v155, v152, v70
	v_pk_mul_f16 v156, v152, v71
	v_pk_fma_f16 v153, v214, v64, v153
	v_pk_fma_f16 v154, v214, v65, v154
	v_pk_fma_f16 v155, v214, v66, v155
	v_pk_fma_f16 v156, v214, v67, v156
	v_pk_fma_f16 v127, v127, v60, v153
	v_pk_fma_f16 v126, v126, v61, v154
	v_pk_fma_f16 v125, v125, v62, v155
	v_pk_fma_f16 v124, v124, v63, v156
	s_waitcnt lgkmcnt(7)
	v_dot2_f32_f16 v151, v127, v134, 0
	v_dot2_f32_f16 v151, v126, v135, v151
	v_dot2_f32_f16 v151, v125, v136, v151
	v_dot2_f32_f16 v151, v124, v137, v151
	v_dot2_f32_f16 v157, v127, v56, 0
	v_dot2_f32_f16 v157, v126, v57, v157
	v_dot2_f32_f16 v157, v125, v58, v157
	v_dot2_f32_f16 v157, v124, v59, v157
	v_add_f32_dpp v151, v151, v151 quad_perm:[1,0,3,2] row_mask:0xf bank_mask:0xf bound_ctrl:1
	ds_read_b128 v[72:75], v114 offset:43136
	ds_read_b128 v[68:71], v114 offset:47232
	v_add_f32_dpp v151, v151, v151 quad_perm:[2,3,0,1] row_mask:0xf bank_mask:0xf bound_ctrl:1
	ds_read_b128 v[64:67], v114 offset:51328
	ds_read_b128 v[60:63], v167 offset:30848
	ds_read_b128 v[56:59], v114 offset:55424
	v_add_f32_dpp v151, v151, v151 row_half_mirror row_mask:0xf bank_mask:0xf bound_ctrl:1
	v_cvt_pkrtz_f16_f32 v152, -v151, -v151
	v_pk_mul_f16 v153, v152, v138
	v_pk_mul_f16 v154, v152, v139
	v_pk_mul_f16 v155, v152, v140
	v_pk_mul_f16 v156, v152, v141
	v_pk_fma_f16 v153, v215, v142, v153
	v_pk_fma_f16 v154, v215, v143, v154
	v_pk_fma_f16 v155, v215, v144, v155
	v_pk_fma_f16 v156, v215, v145, v156
	v_pk_fma_f16 v127, v127, v130, v153
	v_pk_fma_f16 v126, v126, v131, v154
	v_pk_fma_f16 v125, v125, v132, v155
	v_pk_fma_f16 v124, v124, v133, v156
	s_waitcnt lgkmcnt(6)
	v_dot2_f32_f16 v151, v127, v224, 0
	v_dot2_f32_f16 v151, v126, v225, v151
	v_dot2_f32_f16 v151, v125, v226, v151
	v_dot2_f32_f16 v151, v124, v227, v151
	v_dot2_f32_f16 v158, v127, v146, 0
	v_dot2_f32_f16 v158, v126, v147, v158
	v_dot2_f32_f16 v158, v125, v148, v158
	v_dot2_f32_f16 v158, v124, v149, v158
	v_add_f32_dpp v151, v151, v151 quad_perm:[1,0,3,2] row_mask:0xf bank_mask:0xf bound_ctrl:1
	s_nop 1
	v_add_f32_dpp v151, v151, v151 quad_perm:[2,3,0,1] row_mask:0xf bank_mask:0xf bound_ctrl:1
	ds_write2st64_b32 v116, v157, v158 offset0:96 offset1:104
	s_nop 0
	v_add_f32_dpp v151, v151, v151 row_half_mirror row_mask:0xf bank_mask:0xf bound_ctrl:1
	v_cvt_pkrtz_f16_f32 v152, -v151, -v151
	v_pk_mul_f16 v153, v152, v228
	v_pk_mul_f16 v154, v152, v229
	v_pk_mul_f16 v155, v152, v230
	v_pk_mul_f16 v156, v152, v231
	v_pk_fma_f16 v153, v216, v232, v153
	v_pk_fma_f16 v154, v216, v233, v154
	v_pk_fma_f16 v155, v216, v234, v155
	v_pk_fma_f16 v156, v216, v235, v156
	v_pk_fma_f16 v127, v127, v220, v153
	v_pk_fma_f16 v126, v126, v221, v154
	v_pk_fma_f16 v125, v125, v222, v155
	v_pk_fma_f16 v124, v124, v223, v156
	s_waitcnt lgkmcnt(1)
	v_dot2_f32_f16 v151, v127, v72, 0
	v_dot2_f32_f16 v151, v126, v73, v151
	v_dot2_f32_f16 v151, v125, v74, v151
	v_dot2_f32_f16 v151, v124, v75, v151
	v_dot2_f32_f16 v157, v127, v236, 0
	v_dot2_f32_f16 v157, v126, v237, v157
	v_dot2_f32_f16 v157, v125, v238, v157
	v_dot2_f32_f16 v157, v124, v239, v157
	v_add_f32_dpp v151, v151, v151 quad_perm:[1,0,3,2] row_mask:0xf bank_mask:0xf bound_ctrl:1
	s_nop 1
	v_add_f32_dpp v151, v151, v151 quad_perm:[2,3,0,1] row_mask:0xf bank_mask:0xf bound_ctrl:1
	s_nop 1
	v_add_f32_dpp v151, v151, v151 row_half_mirror row_mask:0xf bank_mask:0xf bound_ctrl:1
	v_cvt_pkrtz_f16_f32 v152, -v151, -v151
	v_pk_mul_f16 v153, v152, v68
	v_pk_mul_f16 v154, v152, v69
	v_pk_mul_f16 v155, v152, v70
	v_pk_mul_f16 v156, v152, v71
	v_pk_fma_f16 v153, v217, v64, v153
	v_pk_fma_f16 v154, v217, v65, v154
	v_pk_fma_f16 v155, v217, v66, v155
	v_pk_fma_f16 v156, v217, v67, v156
	v_pk_fma_f16 v127, v127, v60, v153
	v_pk_fma_f16 v126, v126, v61, v154
	v_pk_fma_f16 v125, v125, v62, v155
	v_pk_fma_f16 v124, v124, v63, v156
	v_dot2_f32_f16 v158, v127, v56, 0
	v_dot2_f32_f16 v158, v126, v57, v158
	v_dot2_f32_f16 v158, v125, v58, v158
	v_dot2_f32_f16 v158, v124, v59, v158
	s_nop 2
	ds_write2st64_b32 v116, v157, v158 offset0:112 offset1:120
	s_xor_b32 s100, s100, 0xe100
	s_cmpk_lg_i32 s30, 0x80
	s_cbranch_scc0 .LBB0_1250
	s_mov_b32 s4, s30
	s_and_saveexec_b64 s[18:19], s[10:11]
	s_cbranch_execnz .LBB0_1229
	s_branch .LBB0_1230
